# v23 + attention-unit output stores write-back (no sc1) instead of write-through
# baseline (speedup 1.0000x reference)
; template <int OFF = 0, class V> __device__ __forceinline__ void st_wt16(void* p, V v) { static_assert(sizeof(V) == 16, ""); asm volatile("global_store_dwordx4 %0, %1, off offset:%2 sc1\n\ts_nop 1" :: "v"(p), "v"(v), "i"(OFF)); }
; #define ALAS __attribute__((address_space(3)))
; __device__ __forceinline__ int crow(int r, int hi) { return (r & 3) + 8 * (r >> 2) + 4 * hi; }
; __device__ __forceinline__ unsigned cvtpk(float lo, float hi) { unsigned r; asm volatile("v_cvt_pk_bf16_f32 %0, %1, %2" : "=v"(r) : "v"(lo), "v"(hi)); return r; }
; template <int LD, class FillFn> ...
;     ...
;   if (hi == 0) li_l[r32] = l_reg; asm volatile("s_waitcnt lgkmcnt(0)" ::: "memory");
;   float rli[16];
; #pragma unroll
;   for (int r = 0; r < 16; ++r) rli[r] = __builtin_amdgcn_rcpf(li_l[crow(r, hi)]);
;   { lptr stg = lds + OFF_STG + wid * 4096; const int psh = (mode == MODE_D) ? 10 : 12;
;     bf16* Ob = (bf16*)Op + ((unsigned)(wid * QBLK) << psh);
; #pragma unroll
;     for (int p = 0; p < 2; ++p) {
; #pragma unroll
;       for (int r = 0; r < 16; ++r) { const unsigned w = cvtpk(o[2 * p][r] * rli[r], o[2 * p + 1][r] * rli[r]); ALAS unsigned short* sp = (ALAS unsigned short*)(stg + crow(r, hi) * 128 + r32 * 2);
;         sp[0] = (unsigned short)w; sp[32] = (unsigned short)(w >> 16); }
;       asm volatile("s_waitcnt lgkmcnt(0)" ::: "memory");
; #pragma unroll
;       for (int i = 0; i < 4; ++i) { const int row = i * 8 + (lane >> 3), ch = lane & 7; const u32x4 v = *(const ALAS u32x4*)(stg + row * 128 + ch * 16);
;         st_wt16(Ob + (((unsigned)row << psh) + p * 64 + ch * 8), v); }
;       asm volatile("s_waitcnt lgkmcnt(0)" ::: "memory"); } }
.LBB0_332:
	s_or_b64 exec, exec, s[2:3]
	s_waitcnt lgkmcnt(0)
	v_add_u32_e32 v72, s31, v224
	ds_read_b128 v[64:67], v72
	ds_read_b128 v[68:71], v72 offset:32
	s_lshl_b32 s1, s41, 12
	s_add_i32 s1, s1, 0
	s_add_i32 s1, s1, 0x12800
	s_waitcnt lgkmcnt(1)
	v_rcp_f32_e32 v73, v64
	v_rcp_f32_e32 v74, v65
	v_rcp_f32_e32 v75, v66
	v_rcp_f32_e32 v76, v67
	s_waitcnt lgkmcnt(0)
	v_rcp_f32_e32 v77, v68
	ds_read_b128 v[64:67], v72 offset:64
	v_rcp_f32_e32 v78, v69
	v_rcp_f32_e32 v79, v70
	v_rcp_f32_e32 v80, v71
	ds_read_b128 v[68:71], v72 offset:96
	v_lshlrev_b32_e32 v72, 9, v222
	v_lshlrev_b32_e32 v81, 1, v221
	v_mul_f32_e32 v32, v32, v73
	v_add3_u32 v72, s1, v72, v81
	v_mul_f32_e32 v48, v48, v73
	v_cvt_pk_bf16_f32 v32, v48, v32
	ds_write_b16 v72, v32
	ds_write_b16_d16_hi v72, v32 offset:64
	v_mul_f32_e32 v32, v49, v74
	v_mul_f32_e32 v33, v33, v74
	v_cvt_pk_bf16_f32 v32, v32, v33
	ds_write_b16 v72, v32 offset:128
	ds_write_b16_d16_hi v72, v32 offset:192
	v_mul_f32_e32 v32, v50, v75
	v_mul_f32_e32 v33, v34, v75
	v_cvt_pk_bf16_f32 v32, v32, v33
	ds_write_b16 v72, v32 offset:256
	ds_write_b16_d16_hi v72, v32 offset:320
	v_mul_f32_e32 v32, v51, v76
	v_mul_f32_e32 v33, v35, v76
	v_cvt_pk_bf16_f32 v32, v32, v33
	ds_write_b16 v72, v32 offset:384
	ds_write_b16_d16_hi v72, v32 offset:448
	v_mul_f32_e32 v32, v52, v77
	v_mul_f32_e32 v33, v36, v77
	v_cvt_pk_bf16_f32 v32, v32, v33
	ds_write_b16 v72, v32 offset:1024
	ds_write_b16_d16_hi v72, v32 offset:1088
	v_mul_f32_e32 v32, v53, v78
	v_mul_f32_e32 v33, v37, v78
	v_cvt_pk_bf16_f32 v32, v32, v33
	s_waitcnt lgkmcnt(11)
	v_rcp_f32_e32 v64, v64
	ds_write_b16 v72, v32 offset:1152
	ds_write_b16_d16_hi v72, v32 offset:1216
	v_mul_f32_e32 v32, v54, v79
	v_mul_f32_e32 v33, v38, v79
	v_cvt_pk_bf16_f32 v32, v32, v33
	v_rcp_f32_e32 v65, v65
	ds_write_b16 v72, v32 offset:1280
	ds_write_b16_d16_hi v72, v32 offset:1344
	v_mul_f32_e32 v32, v55, v80
	v_mul_f32_e32 v33, v39, v80
	v_cvt_pk_bf16_f32 v32, v32, v33
	v_rcp_f32_e32 v66, v66
	ds_write_b16 v72, v32 offset:1408
	ds_write_b16_d16_hi v72, v32 offset:1472
	v_mul_f32_e32 v32, v56, v64
	v_mul_f32_e32 v33, v40, v64
	v_cvt_pk_bf16_f32 v32, v32, v33
	v_rcp_f32_e32 v67, v67
	ds_write_b16 v72, v32 offset:2048
	ds_write_b16_d16_hi v72, v32 offset:2112
	v_mul_f32_e32 v32, v57, v65
	v_mul_f32_e32 v33, v41, v65
	v_cvt_pk_bf16_f32 v32, v32, v33
	s_waitcnt lgkmcnt(14)
	v_rcp_f32_e32 v68, v68
	ds_write_b16 v72, v32 offset:2176
	ds_write_b16_d16_hi v72, v32 offset:2240
	v_mul_f32_e32 v32, v58, v66
	v_mul_f32_e32 v33, v42, v66
	v_cvt_pk_bf16_f32 v32, v32, v33
	v_rcp_f32_e32 v69, v69
	ds_write_b16 v72, v32 offset:2304
	ds_write_b16_d16_hi v72, v32 offset:2368
	v_mul_f32_e32 v32, v59, v67
	v_mul_f32_e32 v33, v43, v67
	v_cvt_pk_bf16_f32 v32, v32, v33
	v_rcp_f32_e32 v70, v70
	ds_write_b16 v72, v32 offset:2432
	ds_write_b16_d16_hi v72, v32 offset:2496
	v_mul_f32_e32 v32, v60, v68
	v_mul_f32_e32 v33, v44, v68
	v_cvt_pk_bf16_f32 v32, v32, v33
	v_rcp_f32_e32 v71, v71
	ds_write_b16 v72, v32 offset:3072
	ds_write_b16_d16_hi v72, v32 offset:3136
	v_mul_f32_e32 v32, v61, v69
	v_mul_f32_e32 v33, v45, v69
	v_cvt_pk_bf16_f32 v32, v32, v33
	s_and_b64 s[2:3], s[24:25], exec
	ds_write_b16 v72, v32 offset:3200
	ds_write_b16_d16_hi v72, v32 offset:3264
	v_mul_f32_e32 v32, v62, v70
	s_cselect_b32 s4, 10, 12
	v_mul_f32_e32 v33, v46, v70
	v_cvt_pk_bf16_f32 v32, v32, v33
	s_lshl_b32 s12, s40, s4
	ds_write_b16 v72, v32 offset:3328
	ds_write_b16_d16_hi v72, v32 offset:3392
	v_mul_f32_e32 v32, v63, v71
	s_lshl_b64 s[2:3], s[12:13], 1
	v_readlane_b32 s8, v255, 14
	v_lshrrev_b32_e32 v81, 3, v200
	v_mul_f32_e32 v33, v47, v71
	v_cvt_pk_bf16_f32 v32, v32, v33
	v_lshlrev_b32_e32 v42, 3, v223
	v_readlane_b32 s9, v255, 15
	s_add_u32 s2, s8, s2
	v_lshl_add_u32 v82, v223, 4, s1
	ds_write_b16 v72, v32 offset:3456
	ds_write_b16_d16_hi v72, v32 offset:3520
	v_lshl_or_b32 v36, v81, s4, v42
	v_or_b32_e32 v38, 8, v81
	s_addc_u32 s3, s9, s3
	v_lshl_add_u32 v83, v81, 7, v82
	s_waitcnt lgkmcnt(0)
	v_lshlrev_b32_e32 v200, 1, v36
	v_lshl_add_u32 v44, v38, 7, v82
	v_lshl_or_b32 v38, v38, s4, v42
	v_or_b32_e32 v40, 16, v81
	ds_read_b128 v[32:35], v83
	v_lshl_add_u64 v[36:37], s[2:3], 0, v[200:201]
	v_lshlrev_b32_e32 v200, 1, v38
	v_lshl_add_u32 v45, v40, 7, v82
	v_lshl_or_b32 v40, v40, s4, v42
	v_or_b32_e32 v43, 24, v81
	s_waitcnt lgkmcnt(0)
; template <int OFF = 0, class V> __device__ __forceinline__ void st_wt16(void* p, V v) { static_assert(sizeof(V) == 16, ""); asm volatile("global_store_dwordx4 %0, %1, off offset:%2 sc1\n\ts_nop 1" :: "v"(p), "v"(v), "i"(OFF)); }
; #define ALAS __attribute__((address_space(3)))
; __device__ __forceinline__ int crow(int r, int hi) { return (r & 3) + 8 * (r >> 2) + 4 * hi; }
; __device__ __forceinline__ unsigned cvtpk(float lo, float hi) { unsigned r; asm volatile("v_cvt_pk_bf16_f32 %0, %1, %2" : "=v"(r) : "v"(lo), "v"(hi)); return r; }
; template <int LD, class FillFn> ...
;     ...
;     for (int p = 0; p < 2; ++p) {
; #pragma unroll
;       for (int r = 0; r < 16; ++r) { const unsigned w = cvtpk(o[2 * p][r] * rli[r], o[2 * p + 1][r] * rli[r]); ALAS unsigned short* sp = (ALAS unsigned short*)(stg + crow(r, hi) * 128 + r32 * 2);
;         sp[0] = (unsigned short)w; sp[32] = (unsigned short)(w >> 16); }
;       asm volatile("s_waitcnt lgkmcnt(0)" ::: "memory");
; #pragma unroll
;       for (int i = 0; i < 4; ++i) { const int row = i * 8 + (lane >> 3), ch = lane & 7; const u32x4 v = *(const ALAS u32x4*)(stg + row * 128 + ch * 16);
;         st_wt16(Ob + (((unsigned)row << psh) + p * 64 + ch * 8), v); }
;       asm volatile("s_waitcnt lgkmcnt(0)" ::: "memory"); } }
	global_store_dwordx4 v[36:37], v[32:35], off offset:0
	s_nop 1
	ds_read_b128 v[32:35], v44
	v_lshl_add_u64 v[38:39], s[2:3], 0, v[200:201]
	v_lshlrev_b32_e32 v200, 1, v40
	v_lshl_or_b32 v42, v43, s4, v42
	s_waitcnt lgkmcnt(0)
	global_store_dwordx4 v[38:39], v[32:35], off offset:0
	s_nop 1
	ds_read_b128 v[32:35], v45
	v_lshl_add_u64 v[40:41], s[2:3], 0, v[200:201]
	v_lshl_add_u32 v46, v43, 7, v82
	v_lshlrev_b32_e32 v200, 1, v42
	v_mul_f32_e32 v0, v0, v73
	s_waitcnt lgkmcnt(0)
	global_store_dwordx4 v[40:41], v[32:35], off offset:0
	s_nop 1
	ds_read_b128 v[32:35], v46
	v_lshl_add_u64 v[42:43], s[2:3], 0, v[200:201]
	s_waitcnt lgkmcnt(0)
	global_store_dwordx4 v[42:43], v[32:35], off offset:0
	s_nop 1
	s_waitcnt lgkmcnt(0)
	v_mul_f32_e32 v16, v16, v73
	v_cvt_pk_bf16_f32 v0, v16, v0
	ds_write_b16 v72, v0
	ds_write_b16_d16_hi v72, v0 offset:64
	v_mul_f32_e32 v0, v17, v74
	v_mul_f32_e32 v1, v1, v74
	v_cvt_pk_bf16_f32 v0, v0, v1
	ds_write_b16 v72, v0 offset:128
	ds_write_b16_d16_hi v72, v0 offset:192
	v_mul_f32_e32 v0, v18, v75
	v_mul_f32_e32 v1, v2, v75
	v_cvt_pk_bf16_f32 v0, v0, v1
	ds_write_b16 v72, v0 offset:256
	ds_write_b16_d16_hi v72, v0 offset:320
	v_mul_f32_e32 v0, v19, v76
	v_mul_f32_e32 v1, v3, v76
	v_cvt_pk_bf16_f32 v0, v0, v1
	ds_write_b16 v72, v0 offset:384
	ds_write_b16_d16_hi v72, v0 offset:448
	v_mul_f32_e32 v0, v20, v77
	v_mul_f32_e32 v1, v4, v77
	v_cvt_pk_bf16_f32 v0, v0, v1
	ds_write_b16 v72, v0 offset:1024
	ds_write_b16_d16_hi v72, v0 offset:1088
	v_mul_f32_e32 v0, v21, v78
	v_mul_f32_e32 v1, v5, v78
	v_cvt_pk_bf16_f32 v0, v0, v1
	ds_write_b16 v72, v0 offset:1152
	ds_write_b16_d16_hi v72, v0 offset:1216
	v_mul_f32_e32 v0, v22, v79
	v_mul_f32_e32 v1, v6, v79
	v_cvt_pk_bf16_f32 v0, v0, v1
	ds_write_b16 v72, v0 offset:1280
	ds_write_b16_d16_hi v72, v0 offset:1344
	v_mul_f32_e32 v0, v23, v80
	v_mul_f32_e32 v1, v7, v80
	v_cvt_pk_bf16_f32 v0, v0, v1
	ds_write_b16 v72, v0 offset:1408
	ds_write_b16_d16_hi v72, v0 offset:1472
	v_mul_f32_e32 v0, v24, v64
	v_mul_f32_e32 v1, v8, v64
	v_cvt_pk_bf16_f32 v0, v0, v1
	ds_write_b16 v72, v0 offset:2048
	ds_write_b16_d16_hi v72, v0 offset:2112
	v_mul_f32_e32 v0, v25, v65
	v_mul_f32_e32 v1, v9, v65
	v_cvt_pk_bf16_f32 v0, v0, v1
	ds_write_b16 v72, v0 offset:2176
	ds_write_b16_d16_hi v72, v0 offset:2240
	v_mul_f32_e32 v0, v26, v66
	v_mul_f32_e32 v1, v10, v66
	v_cvt_pk_bf16_f32 v0, v0, v1
	ds_write_b16 v72, v0 offset:2304
	ds_write_b16_d16_hi v72, v0 offset:2368
	v_mul_f32_e32 v0, v27, v67
	v_mul_f32_e32 v1, v11, v67
	v_cvt_pk_bf16_f32 v0, v0, v1
	ds_write_b16 v72, v0 offset:2432
	ds_write_b16_d16_hi v72, v0 offset:2496
	v_mul_f32_e32 v0, v28, v68
	v_mul_f32_e32 v1, v12, v68
	v_cvt_pk_bf16_f32 v0, v0, v1
	ds_write_b16 v72, v0 offset:3072
	ds_write_b16_d16_hi v72, v0 offset:3136
	v_mul_f32_e32 v0, v29, v69
	v_mul_f32_e32 v1, v13, v69
	v_cvt_pk_bf16_f32 v0, v0, v1
	ds_write_b16 v72, v0 offset:3200
	ds_write_b16_d16_hi v72, v0 offset:3264
	v_mul_f32_e32 v0, v30, v70
	v_mul_f32_e32 v1, v14, v70
	v_cvt_pk_bf16_f32 v0, v0, v1
	ds_write_b16 v72, v0 offset:3328
	ds_write_b16_d16_hi v72, v0 offset:3392
	v_mul_f32_e32 v0, v31, v71
	v_mul_f32_e32 v1, v15, v71
	v_cvt_pk_bf16_f32 v0, v0, v1
	ds_write_b16 v72, v0 offset:3456
	ds_write_b16_d16_hi v72, v0 offset:3520
	s_waitcnt lgkmcnt(0)
	ds_read_b128 v[0:3], v83
	v_lshl_add_u64 v[4:5], v[36:37], 0, s[34:35]
	s_waitcnt lgkmcnt(0)
	global_store_dwordx4 v[4:5], v[0:3], off offset:0
	s_nop 1
	ds_read_b128 v[0:3], v44
	v_lshl_add_u64 v[4:5], v[38:39], 0, s[34:35]
	s_waitcnt lgkmcnt(0)
	global_store_dwordx4 v[4:5], v[0:3], off offset:0
	s_nop 1
	ds_read_b128 v[0:3], v45
	v_lshl_add_u64 v[4:5], v[40:41], 0, s[34:35]
	s_waitcnt lgkmcnt(0)
	global_store_dwordx4 v[4:5], v[0:3], off offset:0
	s_nop 1
	ds_read_b128 v[0:3], v46
	v_lshl_add_u64 v[4:5], v[42:43], 0, s[34:35]
	s_waitcnt lgkmcnt(0)
	global_store_dwordx4 v[4:5], v[0:3], off offset:0
	s_nop 1
	v_readlane_b32 s1, v254, 50
	s_waitcnt lgkmcnt(0)
	s_add_i32 s26, s26, s1
	s_add_i32 s10, s10, 1
	s_cmpk_gt_i32 s26, 0x4ff
	s_cbranch_scc1 .LBB0_520
